# relay-skip only (plain stores, wbl2 kept): last XCD leader releases all XCD generation words
# baseline (speedup 1.0000x reference)
.LBB0_461:
	s_andn2_saveexec_b64 s[4:5], s[4:5]
	s_cbranch_execz .LBB0_481
	s_mov_b64 s[4:5], exec
	v_mov_b32_e32 v8, v3
	buffer_wbl2 sc1
	s_waitcnt lgkmcnt(0)
	s_waitcnt vmcnt(0)
	v_mbcnt_lo_u32_b32 v3, s4, 0
	v_mbcnt_hi_u32_b32 v3, s5, v3
	v_cmp_eq_u32_e32 vcc, 0, v3
	s_and_saveexec_b64 s[6:7], vcc
	s_cbranch_execz .LBB0_464
	s_bcnt1_i32_b64 s4, s[4:5]
	v_mov_b32_e32 v5, s4
	v_readlane_b32 s4, v253, 9
	v_readlane_b32 s5, v253, 10
	s_nop 4
	global_atomic_add v5, v4, v5, s[4:5] sc0

.LBB0_551:
	s_andn2_saveexec_b64 s[6:7], s[6:7]
	s_cbranch_execz .LBB0_571
	s_mov_b64 s[6:7], exec
	v_mov_b32_e32 v8, v3
	buffer_wbl2 sc1
	s_waitcnt lgkmcnt(0)
	s_waitcnt vmcnt(0)
	v_mbcnt_lo_u32_b32 v3, s6, 0
	v_mbcnt_hi_u32_b32 v3, s7, v3
	v_cmp_eq_u32_e32 vcc, 0, v3
	s_and_saveexec_b64 s[8:9], vcc
	s_cbranch_execz .LBB0_554
	s_bcnt1_i32_b64 s6, s[6:7]
	v_mov_b32_e32 v5, s6
	v_readlane_b32 s6, v253, 9
	v_readlane_b32 s7, v253, 10
	s_nop 4
	global_atomic_add v5, v4, v5, s[6:7] sc0
